# stack: ALIGN removal + row-scale reload with all 8 loads in flight + 64-lane K^T transposition in mLSTM (permlane32_swap)
# baseline (speedup 1.0000x reference)
; #define LAS __attribute__((address_space(3)))
; template <class Epi, bool ALIGN_EPI>
; __device__ __forceinline__ void gemm_phase(LAS unsigned char* lds, const Gemm g, const StaticOrder& S, const Epi& E) {
;     ...
;             if (cur.pm != cpm) { cpm = cur.pm; const float* rp = E.rs_src();
; #pragma unroll
;                 for (int j = 0; j < 2; ++j) { const int q = lane + 64 * j; const int row = cur.pm * 256 + (q >> 6) * 128 + wr * 64 + (q & 63);
;                     const f32x4* p4 = (const f32x4*)(rp + (size_t)row * 16); const f32x4 t4 = (p4[0] + p4[1]) + (p4[2] + p4[3]);
;                     ((LAS float*)(lds + RSL_OFF))[wid * 128 + q] = rsqrtf(((t4[0] + t4[1]) + (t4[2] + t4[3])) * (1.0f / 1024.0f) + 1e-6f); } }
.LBB0_105:
	s_lshl_b32 s3, s48, 8
	s_cmp_eq_u32 s48, s1
	s_cbranch_scc1 .LBB0_107
	v_add_u32_e32 v152, s3, v149
	v_ashrrev_i32_e32 v153, 31, v152
	v_readlane_b32 s4, v254, 53
	v_lshlrev_b64 v[140:141], 6, v[152:153]
	v_readlane_b32 s5, v254, 54
	s_mov_b32 s2, 0x3a800000
	s_mov_b32 s1, 0x800000
	v_lshl_add_u64 v[160:161], s[4:5], 0, v[140:141]
	global_load_dwordx4 v[140:143], v[160:161], off offset:32
	global_load_dwordx4 v[144:147], v[160:161], off offset:48
	global_load_dwordx4 v[156:159], v[160:161], off
	s_nop 0
	global_load_dwordx4 v[160:163], v[160:161], off offset:16
	v_add_u32_e32 v200, 0x80, v152
	v_ashrrev_i32_e32 v201, 31, v200
	v_lshlrev_b64 v[200:201], 6, v[200:201]
	v_lshl_add_u64 v[202:203], s[4:5], 0, v[200:201]
	global_load_dwordx4 v[184:187], v[202:203], off offset:32
	global_load_dwordx4 v[188:191], v[202:203], off offset:48
	global_load_dwordx4 v[192:195], v[202:203], off
	global_load_dwordx4 v[196:199], v[202:203], off offset:16
	s_waitcnt vmcnt(4)
	v_pk_add_f32 v[142:143], v[142:143], v[146:147]
	v_pk_add_f32 v[140:141], v[140:141], v[144:145]
	v_pk_add_f32 v[158:159], v[158:159], v[162:163]
	v_pk_add_f32 v[156:157], v[156:157], v[160:161]
	v_pk_add_f32 v[142:143], v[158:159], v[142:143]
	v_pk_add_f32 v[140:141], v[156:157], v[140:141]
	s_nop 0
	v_pk_mov_b32 v[144:145], v[140:141], v[142:143] op_sel:[1,0]
	v_mov_b32_e32 v141, v143
	v_pk_add_f32 v[164:165], v[144:145], v[140:141]
	s_waitcnt vmcnt(2)
	v_pk_add_f32 v[142:143], v[186:187], v[190:191]
	v_pk_add_f32 v[140:141], v[184:185], v[188:189]
	s_waitcnt vmcnt(0)
	v_pk_add_f32 v[152:153], v[194:195], v[198:199]
	v_pk_add_f32 v[156:157], v[192:193], v[196:197]
	v_pk_add_f32 v[142:143], v[152:153], v[142:143]
	v_pk_add_f32 v[140:141], v[156:157], v[140:141]
	s_nop 0
	v_pk_mov_b32 v[144:145], v[140:141], v[142:143] op_sel:[1,0]
	v_mov_b32_e32 v141, v143
	v_pk_add_f32 v[140:141], v[144:145], v[140:141]
	v_mov_b32_e32 v143, v164
	v_mov_b32_e32 v142, v140
	v_mov_b32_e32 v164, v141
	v_pk_add_f32 v[140:141], v[142:143], v[164:165]
	s_nop 0
	v_pk_fma_f32 v[140:141], v[140:141], s[2:3], v[154:155] op_sel_hi:[1,0,0]
	s_nop 0
	v_mul_f32_e32 v142, 0x4b800000, v141
	v_cmp_gt_f32_e64 s[6:7], s1, v141
	v_cmp_gt_f32_e32 vcc, s1, v140
	s_nop 0
	v_cndmask_b32_e64 v141, v141, v142, s[6:7]
	v_rsq_f32_e32 v141, v141
	s_nop 0
	v_mul_f32_e32 v142, 0x45800000, v141
	v_cndmask_b32_e64 v141, v141, v142, s[6:7]
	v_mul_f32_e32 v142, 0x4b800000, v140
	v_cndmask_b32_e32 v140, v140, v142, vcc
	v_rsq_f32_e32 v140, v140
	s_nop 0
	v_mul_f32_e32 v142, 0x45800000, v140
	v_cndmask_b32_e32 v140, v140, v142, vcc
	ds_write2st64_b32 v151, v141, v140 offset1:1

; #define LAS __attribute__((address_space(3)))
; template <class Epi, bool ALIGN_EPI>
; __device__ __forceinline__ void gemm_phase(LAS unsigned char* lds, const Gemm g, const StaticOrder& S, const Epi& E) {
;     ...
;             if (cur.pm != cpm) { cpm = cur.pm; const float* rp = E.rs_src();
; #pragma unroll
;                 for (int j = 0; j < 2; ++j) { const int q = lane + 64 * j; const int row = cur.pm * 256 + (q >> 6) * 128 + wr * 64 + (q & 63);
;                     const f32x4* p4 = (const f32x4*)(rp + (size_t)row * 16); const f32x4 t4 = (p4[0] + p4[1]) + (p4[2] + p4[3]);
;                     ((LAS float*)(lds + RSL_OFF))[wid * 128 + q] = rsqrtf(((t4[0] + t4[1]) + (t4[2] + t4[3])) * (1.0f / 1024.0f) + 1e-6f); } }
.LBB0_307:
	s_lshl_b32 s1, s31, 8
	s_cmp_eq_u32 s31, s35
	s_cbranch_scc1 .LBB0_309
	v_add_u32_e32 v152, s1, v145
	v_ashrrev_i32_e32 v153, 31, v152
	v_readlane_b32 s6, v254, 51
	v_lshlrev_b64 v[140:141], 6, v[152:153]
	v_readlane_b32 s7, v254, 52
	s_nop 1
	v_lshl_add_u64 v[160:161], s[6:7], 0, v[140:141]
	global_load_dwordx4 v[140:143], v[160:161], off offset:32
	global_load_dwordx4 v[148:151], v[160:161], off offset:48
	global_load_dwordx4 v[156:159], v[160:161], off
	global_load_dwordx4 v[180:183], v[160:161], off offset:16
	v_add_u32_e32 v200, 0x80, v152
	v_ashrrev_i32_e32 v201, 31, v200
	v_lshlrev_b64 v[200:201], 6, v[200:201]
	v_lshl_add_u64 v[202:203], s[6:7], 0, v[200:201]
	global_load_dwordx4 v[184:187], v[202:203], off offset:32
	global_load_dwordx4 v[188:191], v[202:203], off offset:48
	global_load_dwordx4 v[192:195], v[202:203], off
	global_load_dwordx4 v[196:199], v[202:203], off offset:16
	s_waitcnt vmcnt(4)
	v_pk_add_f32 v[142:143], v[142:143], v[150:151]
	v_pk_add_f32 v[140:141], v[140:141], v[148:149]
	v_pk_add_f32 v[158:159], v[158:159], v[182:183]
	v_pk_add_f32 v[156:157], v[156:157], v[180:181]
	v_pk_add_f32 v[142:143], v[158:159], v[142:143]
	v_pk_add_f32 v[140:141], v[156:157], v[140:141]
	s_nop 0
	v_pk_mov_b32 v[148:149], v[140:141], v[142:143] op_sel:[1,0]
	v_mov_b32_e32 v141, v143
	v_pk_add_f32 v[160:161], v[148:149], v[140:141]
	s_mov_b32 s6, 0x3a800000
	s_waitcnt vmcnt(2)
	v_pk_add_f32 v[142:143], v[186:187], v[190:191]
	v_pk_add_f32 v[140:141], v[184:185], v[188:189]
	s_waitcnt vmcnt(0)
	v_pk_add_f32 v[152:153], v[194:195], v[198:199]
	v_pk_add_f32 v[156:157], v[192:193], v[196:197]
	v_pk_add_f32 v[142:143], v[152:153], v[142:143]
	v_pk_add_f32 v[140:141], v[156:157], v[140:141]
	s_nop 0
	v_pk_mov_b32 v[148:149], v[140:141], v[142:143] op_sel:[1,0]
	v_mov_b32_e32 v141, v143
	v_pk_add_f32 v[140:141], v[148:149], v[140:141]
	v_mov_b32_e32 v143, v160
	v_mov_b32_e32 v142, v140
	v_mov_b32_e32 v160, v141
	v_pk_add_f32 v[140:141], v[142:143], v[160:161]
	s_nop 0
	v_pk_fma_f32 v[140:141], v[140:141], s[6:7], v[154:155] op_sel_hi:[1,0,0]
	s_mov_b32 s6, 0x800000
	v_mul_f32_e32 v142, 0x4b800000, v141
	v_cmp_gt_f32_e32 vcc, s6, v140
	v_cmp_gt_f32_e64 s[6:7], s6, v141
	s_nop 1
	v_cndmask_b32_e64 v141, v141, v142, s[6:7]
	v_rsq_f32_e32 v141, v141
	s_nop 0
	v_mul_f32_e32 v142, 0x45800000, v141
	v_cndmask_b32_e64 v141, v141, v142, s[6:7]
	v_mul_f32_e32 v142, 0x4b800000, v140
	v_cndmask_b32_e32 v140, v140, v142, vcc
	v_rsq_f32_e32 v140, v140
	s_nop 0
	v_mul_f32_e32 v142, 0x45800000, v140
	v_cndmask_b32_e32 v140, v140, v142, vcc
	ds_write2st64_b32 v147, v141, v140 offset1:1

; #define LAS __attribute__((address_space(3)))
; template <class Epi, bool ALIGN_EPI>
; __device__ __forceinline__ void gemm_phase(LAS unsigned char* lds, const Gemm g, const StaticOrder& S, const Epi& E) {
;     ...
;             if (cur.pm != cpm) { cpm = cur.pm; const float* rp = E.rs_src();
; #pragma unroll
;                 for (int j = 0; j < 2; ++j) { const int q = lane + 64 * j; const int row = cur.pm * 256 + (q >> 6) * 128 + wr * 64 + (q & 63);
;                     const f32x4* p4 = (const f32x4*)(rp + (size_t)row * 16); const f32x4 t4 = (p4[0] + p4[1]) + (p4[2] + p4[3]);
;                     ((LAS float*)(lds + RSL_OFF))[wid * 128 + q] = rsqrtf(((t4[0] + t4[1]) + (t4[2] + t4[3])) * (1.0f / 1024.0f) + 1e-6f); } }
.LBB0_486:
	s_lshl_b32 s1, s31, 8
	s_cmp_eq_u32 s31, s35
	s_cbranch_scc1 .LBB0_488
	v_add_u32_e32 v152, s1, v141
	v_ashrrev_i32_e32 v153, 31, v152
	v_readlane_b32 s6, v254, 53
	v_lshlrev_b64 v[144:145], 6, v[152:153]
	v_readlane_b32 s7, v254, 54
	s_nop 1
	v_lshl_add_u64 v[160:161], s[6:7], 0, v[144:145]
	global_load_dwordx4 v[144:147], v[160:161], off offset:32
	global_load_dwordx4 v[148:151], v[160:161], off offset:48
	global_load_dwordx4 v[156:159], v[160:161], off
	global_load_dwordx4 v[180:183], v[160:161], off offset:16
	v_add_u32_e32 v200, 0x80, v152
	v_ashrrev_i32_e32 v201, 31, v200
	v_lshlrev_b64 v[200:201], 6, v[200:201]
	v_lshl_add_u64 v[202:203], s[6:7], 0, v[200:201]
	global_load_dwordx4 v[184:187], v[202:203], off offset:32
	global_load_dwordx4 v[188:191], v[202:203], off offset:48
	global_load_dwordx4 v[192:195], v[202:203], off
	global_load_dwordx4 v[196:199], v[202:203], off offset:16
	s_waitcnt vmcnt(4)
	v_pk_add_f32 v[146:147], v[146:147], v[150:151]
	v_pk_add_f32 v[144:145], v[144:145], v[148:149]
	v_pk_add_f32 v[158:159], v[158:159], v[182:183]
	v_pk_add_f32 v[156:157], v[156:157], v[180:181]
	v_pk_add_f32 v[146:147], v[158:159], v[146:147]
	v_pk_add_f32 v[144:145], v[156:157], v[144:145]
	s_nop 0
	v_pk_mov_b32 v[148:149], v[144:145], v[146:147] op_sel:[1,0]
	v_mov_b32_e32 v145, v147
	v_pk_add_f32 v[160:161], v[148:149], v[144:145]
	s_mov_b32 s6, 0x3a800000
	s_waitcnt vmcnt(2)
	v_pk_add_f32 v[146:147], v[186:187], v[190:191]
	v_pk_add_f32 v[144:145], v[184:185], v[188:189]
	s_waitcnt vmcnt(0)
	v_pk_add_f32 v[152:153], v[194:195], v[198:199]
	v_pk_add_f32 v[156:157], v[192:193], v[196:197]
	v_pk_add_f32 v[146:147], v[152:153], v[146:147]
	v_pk_add_f32 v[144:145], v[156:157], v[144:145]
	s_nop 0
	v_pk_mov_b32 v[148:149], v[144:145], v[146:147] op_sel:[1,0]
	v_mov_b32_e32 v145, v147
	v_pk_add_f32 v[144:145], v[148:149], v[144:145]
	v_mov_b32_e32 v147, v160
	v_mov_b32_e32 v146, v144
	v_mov_b32_e32 v160, v145
	v_pk_add_f32 v[144:145], v[146:147], v[160:161]
	s_nop 0
	v_pk_fma_f32 v[144:145], v[144:145], s[6:7], v[154:155] op_sel_hi:[1,0,0]
	s_mov_b32 s6, 0x800000
	v_mul_f32_e32 v146, 0x4b800000, v145
	v_cmp_gt_f32_e32 vcc, s6, v144
	v_cmp_gt_f32_e64 s[6:7], s6, v145
	s_nop 1
	v_cndmask_b32_e64 v145, v145, v146, s[6:7]
	v_rsq_f32_e32 v145, v145
	s_nop 0
	v_mul_f32_e32 v146, 0x45800000, v145
	v_cndmask_b32_e64 v145, v145, v146, s[6:7]
	v_mul_f32_e32 v146, 0x4b800000, v144
	v_cndmask_b32_e32 v144, v144, v146, vcc
	v_rsq_f32_e32 v144, v144
	s_nop 0
	v_mul_f32_e32 v146, 0x45800000, v144
	v_cndmask_b32_e32 v144, v144, v146, vcc
	ds_write2st64_b32 v143, v145, v144 offset1:1

; __device__ __forceinline__ void mlstm_unit(KArg P, int L, int b, int h, int vs, LAS unsigned char* lds) {
;     ...
;         for (int r = 0; r < 8; ++r) *(LAS v4u*)(lds + (isk ? ML_KS : ML_QS) + (w * 8 + r) * 528 + (cgp & 31) * 16) = raw[r];
;     };
;     auto stage_kt_v = [&](LAS float* gbn) {
;         if (isk) {
; #pragma unroll
;             for (int e = 0; e < 8; ++e) {
;                 v4u t;
;     ...
;                 if (e & 1) { t.x = (PKW(0) >> 16) | (PKW(1) & 0xffff0000u); t.y = (PKW(2) >> 16) | (PKW(3) & 0xffff0000u); t.z = (PKW(4) >> 16) | (PKW(5) & 0xffff0000u); t.w = (PKW(6) >> 16) | (PKW(7) & 0xffff0000u); }
;                 else { t.x = (PKW(0) & 0xffffu) | (PKW(1) << 16); t.y = (PKW(2) & 0xffffu) | (PKW(3) << 16); t.z = (PKW(4) & 0xffffu) | (PKW(5) << 16); t.w = (PKW(6) & 0xffffu) | (PKW(7) << 16); }
;     ...
;                 *(LAS v4u*)(lds + ML_KT + ((cgp & 31) * 8 + e) * 144 + ((w ^ (((cgp & 31) >> 1) & 7)) * 16)) = t; }
;         }
;         if (tid < 256) { const int s = tid >> 2, part = tid & 3; const float ws_ = gbn[FL_WST + s];
;             const unsigned xs[4] = {vraw.x, vraw.y, vraw.z, vraw.w};
; #pragma unroll
;             for (int e = 0; e < 8; ++e) { const unsigned wd = xs[e >> 1]; const float v = (e & 1) ? bfhi(wd) : bflo(wd);
;                 *(LAS bf16*)(lds + ML_VT + (part * 8 + e) * 144 + s * 2) = (bf16)((e & 1) ? (wd >> 16) : (wd & 0xffffu));
;                 *(LAS bf16*)(lds + ML_VWT + (part * 8 + e) * 144 + s * 2) = (bf16)(cvt_pk_bf16(v * ws_, 0.f) & 0xffffu); } }
;     };
;     prefetch(0);
;     if (w == 7) gates(FL);
;     __syncthreads();
;     stage_qk(); stage_kt_v(FL);
;     __syncthreads();
;     const int ttile = w >> 1, par = w & 1;
;     ...
;             const LAS unsigned char* qp = lds + ML_QS + (ttile * 16 + c) * 528 + g * 16;
;             const LAS unsigned char* k0p = lds + ML_KS + ((par * 2 + 0) * 16 + c) * 528 + g * 16;
;             const LAS unsigned char* k1p = lds + ML_KS + ((par * 2 + 1) * 16 + c) * 528 + g * 16;
;             const LAS unsigned char* cp = lds + ML_CB + (par * 16 + c) * 528 + g * 16;
; #pragma unroll 2
;             for (int kk = 0; kk < 8; ++kk) {
;                 const bf16x8 a = *(const LAS bf16x8*)(qp + kk * 64);
;                 const bf16x8 b0 = *(const LAS bf16x8*)(k0p + kk * 64), b1 = *(const LAS bf16x8*)(k1p + kk * 64), bc = *(const LAS bf16x8*)(cp + kk * 64);
.LBB0_519:
	s_or_b64 exec, exec, s[12:13]
	s_lshl_b32 s41, s16, 5
	v_readlane_b32 s16, v254, 20
	v_lshlrev_b32_e32 v52, 4, v0
	v_readlane_b32 s12, v254, 43
	v_mov_b32_e32 v0, s16
	v_readlane_b32 s16, v254, 21
	v_mad_u32_u24 v53, v43, s86, v0
	v_mov_b32_e32 v41, v1
	v_mov_b32_e32 v0, s16
	v_readlane_b32 s16, v254, 22
	v_readlane_b32 s13, v254, 44
	v_mad_u32_u24 v54, v43, s86, v0
	v_mov_b32_e32 v0, s16
	v_readlane_b32 s16, v254, 23
	v_and_b32_e32 v46, 15, v42
	s_bfe_u32 s4, s35, 0x10006
	v_lshl_add_u64 v[84:85], s[12:13], 0, v[40:41]
	v_bfi_b32 v40, -16, s53, v42
	v_mad_u32_u24 v55, v43, s86, v0
	v_mov_b32_e32 v0, s16
	v_readlane_b32 s16, v254, 24
	v_lshrrev_b32_e32 v45, 4, v2
	v_lshl_or_b32 v108, s4, 5, v46
	s_lshl_b32 s4, s4, 4
	v_mul_lo_u32 v40, v40, s86
	v_readlane_b32 s20, v254, 29
	v_readlane_b32 s17, v254, 27
	v_mad_u32_u24 v56, v43, s86, v0
	v_mov_b32_e32 v0, s16
	v_readlane_b32 s16, v254, 25
	v_and_b32_e32 v107, 48, v42
	v_or_b32_e32 v42, s4, v46
	v_lshlrev_b32_e32 v48, 2, v45
	v_add_u32_e32 v49, s20, v40
	v_mov_b32_e32 v40, s17
	v_readlane_b32 s39, v254, 19
	v_mad_u32_u24 v57, v43, s86, v0
	v_mov_b32_e32 v0, s16
	v_readlane_b32 s16, v254, 26
	v_mul_u32_u24_e32 v47, 0x210, v42
	v_and_or_b32 v86, s53, -16, v48
	v_mad_u32_u24 v42, v42, s86, v40
	v_mov_b32_e32 v40, s39
	v_mad_u32_u24 v58, v43, s86, v0
	v_mov_b32_e32 v0, s16
	v_mad_u32_u24 v51, v43, s86, v40
	v_mad_u32_u24 v43, v43, s86, v0
	v_mul_lo_u32 v0, v86, s86
	v_add_u32_e32 v114, s20, v0
	v_lshl_or_b32 v0, s40, 5, v46
	s_lshl_b32 s38, s40, 1
	v_readlane_b32 s18, v254, 28
	v_mul_lo_u32 v0, v0, s86
	s_andn2_b32 s35, s35, 63
	v_or_b32_e32 v48, 16, v108
	v_add_u32_e32 v112, s17, v44
	v_add_u32_e32 v113, s18, v44
	v_or_b32_e32 v88, 1, v86
	v_or_b32_e32 v90, 2, v86
	v_or_b32_e32 v92, 3, v86
	v_add_u32_e32 v44, s39, v0
	v_bitop3_b32 v0, s38, v45, 6 bitop3:0x6c
	s_add_i32 s64, s35, 0
	v_lshlrev_b32_e32 v110, 1, v48
	v_add_u32_e32 v50, s18, v107
	v_cmp_le_i32_e64 s[18:19], v48, v86
	v_cmp_le_i32_e64 s[22:23], v48, v88
	v_cmp_le_i32_e64 s[26:27], v48, v90
	v_cmp_le_i32_e64 s[30:31], v48, v92
	v_lshlrev_b32_e32 v48, 4, v0
	v_or_b32_e32 v0, 4, v45
	v_lshlrev_b32_e32 v118, 1, v46
	s_add_i32 s35, s64, 0x1bc00
	v_bitop3_b32 v40, s38, v0, 6 bitop3:0x6c
	v_add_u32_e32 v60, s35, v118
	s_or_b32 s35, s38, 1
	v_lshlrev_b32_e32 v59, 4, v40
	v_lshl_or_b32 v40, s35, 4, v46
	v_mul_lo_u32 v40, v40, s86
	s_add_i32 s16, 0, 0x22200
	s_add_i32 s63, s64, 0x22e40
	v_add_u32_e32 v63, s39, v40
	v_bitop3_b32 v40, s35, v45, 7 bitop3:0x6c
	v_bitop3_b32 v0, s35, v0, 7 bitop3:0x6c
	s_add_i32 s35, s64, 0x1bc20
	s_add_i32 s64, s64, 0x22e60
	s_lshl_b32 s34, s34, 2
	s_add_u32 s38, s0, s34
	v_mul_u32_u24_e32 v41, 0x210, v108
	s_addc_u32 s39, s1, 0
	s_add_i32 s34, 0, 0x8400
	v_add3_u32 v120, v41, v107, s34
	s_lshr_b32 s34, s40, 1
	v_lshlrev_b32_e32 v64, 4, v0
	v_lshlrev_b32_e32 v0, 1, v2
	s_mulk_i32 s34, 0x2100
	v_sub_u32_e32 v119, 0, v0
	v_mov_b32_e32 v0, s34
	s_movk_i32 s34, 0x210
	v_mul_u32_u24_e32 v61, 0x90, v46
	v_mul_u32_u24_e32 v62, 0x840, v45
	v_lshlrev_b32_e32 v45, 4, v40
	v_add_u32_e32 v65, s35, v118
	v_mad_u32_u24 v0, v46, s34, v0
	v_mov_b32_e32 v40, 0
	v_lshlrev_b32_e32 v109, 1, v108
	v_cmp_gt_u32_e64 s[12:13], 16, v2
	v_ashrrev_i32_e32 v81, 31, v80
	v_mov_b32_e32 v83, v1
	s_mov_b32 s43, 0
	v_cmp_eq_u32_e64 s[14:15], 0, v2
	v_lshl_add_u32 v111, v80, 2, s16
	v_cmp_le_i32_e64 s[16:17], v108, v86
	v_cmp_le_i32_e64 s[20:21], v108, v88
	v_add_u32_e32 v115, 0x90, v114
	v_cmp_le_i32_e64 s[24:25], v108, v90
	v_add_u32_e32 v116, 0x120, v114
	v_cmp_le_i32_e64 s[28:29], v108, v92
	v_add_u32_e32 v117, 0x1b0, v114
	v_ashrrev_i32_e32 v87, 31, v86
	v_ashrrev_i32_e32 v89, 31, v88
	v_ashrrev_i32_e32 v91, 31, v90
	v_ashrrev_i32_e32 v93, 31, v92
	v_add_u32_e32 v121, 0, v107
	v_add3_u32 v122, v47, v107, 0
	v_add3_u32 v123, v0, v107, 0
	v_add_u32_e32 v124, v49, v107
	v_add_u32_e32 v125, v42, v107
	s_lshl_b32 s40, s41, 1
	s_lshl_b32 s42, s4, 1
	v_lshlrev_b32_e32 v0, 1, v46
	v_add_u32_e32 v126, v44, v48
	v_add_u32_e32 v127, v44, v59
	v_add_u32_e32 v128, v60, v62
	v_add_u32_e32 v129, v63, v45
	v_add_u32_e32 v130, v63, v64
	v_add_u32_e32 v131, v65, v62
	v_lshrrev_b32_e32 v246, 2, v46
	v_lshrrev_b32_e32 v247, 3, v46
	v_and_b32_e32 v248, 16, v107
	v_xor_b32_e32 v246, v246, v247
	v_lshlrev_b32_e32 v248, 1, v248
	v_and_b32_e32 v246, 1, v246
	v_sub_u32_e32 v248, 16, v248
	v_cmp_eq_u32_e32 vcc, 1, v246
	s_nop 1
	v_cndmask_b32_e32 v248, 0, v248, vcc
	v_add_u32_e32 v120, v120, v248
	v_add_u32_e32 v122, v122, v248
	v_add_u32_e32 v123, v123, v248
	v_lshrrev_b32_e32 v246, 4, v107
	v_lshrrev_b32_e32 v247, 5, v107
	v_and_b32_e32 v248, 8, v46
	v_xor_b32_e32 v246, v246, v247
	v_lshlrev_b32_e32 v248, 2, v248
	v_and_b32_e32 v246, 1, v246
	v_sub_u32_e32 v248, 16, v248
	v_cmp_eq_u32_e32 vcc, 1, v246
	s_nop 1
	v_cndmask_b32_e32 v248, 0, v248, vcc
	v_add_u32_e32 v128, v128, v248
	v_add_u32_e32 v131, v131, v248
	v_add_u32_e32 v132, v51, v52
	v_add_u32_e32 v133, v53, v52
	v_add_u32_e32 v134, v54, v52
	v_add_u32_e32 v135, v55, v52
	v_add_u32_e32 v136, v56, v52
	v_add_u32_e32 v137, v57, v52
	v_add_u32_e32 v138, v58, v52
	v_add_u32_e32 v139, v43, v52
	v_mov_b32_e32 v249, v132
	v_mov_b32_e32 v253, v136
	s_nop 1
	v_permlane32_swap_b32_e32 v253, v249
	v_mov_b32_e32 v250, v133
	v_mov_b32_e32 v253, v137
	s_nop 1
	v_permlane32_swap_b32_e32 v253, v250
	v_mov_b32_e32 v251, v134
	v_mov_b32_e32 v253, v138
	s_nop 1
	v_permlane32_swap_b32_e32 v253, v251
	v_mov_b32_e32 v252, v135
	v_mov_b32_e32 v253, v139
	s_nop 1
	v_permlane32_swap_b32_e32 v253, v252
	v_add_u32_e32 v140, v50, v61
	v_mov_b32_e32 v41, v40
	v_mov_b32_e32 v42, v40
	v_mov_b32_e32 v43, v40
	v_mov_b32_e32 v52, v40
	v_mov_b32_e32 v53, v40
	v_mov_b32_e32 v54, v40
	v_mov_b32_e32 v55, v40
	v_mov_b32_e32 v48, v40
	v_mov_b32_e32 v49, v40
	v_mov_b32_e32 v50, v40
	v_mov_b32_e32 v51, v40
	v_mov_b32_e32 v60, v40
	v_mov_b32_e32 v61, v40
	v_mov_b32_e32 v62, v40
	v_mov_b32_e32 v63, v40
	v_mov_b32_e32 v56, v40
	v_mov_b32_e32 v57, v40
	v_mov_b32_e32 v58, v40
	v_mov_b32_e32 v59, v40
	v_mov_b32_e32 v44, v40
	v_mov_b32_e32 v45, v40
	v_mov_b32_e32 v46, v40
	v_mov_b32_e32 v47, v40
	s_waitcnt lgkmcnt(0)
	s_barrier
	s_branch .LBB0_522

; #define LAS __attribute__((address_space(3)))
; __device__ __forceinline__ unsigned cvt_pk_bf16(float lo, float hi) { f32x2_t v = {lo, hi}; bf16x2_t b = __builtin_convertvector(v, bf16x2_t); return __builtin_bit_cast(unsigned, b); }
; __device__ __forceinline__ float bflo(unsigned w) { return __uint_as_float(w << 16); }
; __device__ __forceinline__ float bfhi(unsigned w) { return __uint_as_float(w & 0xffff0000u); }
; __device__ __forceinline__ void mlstm_unit(KArg P, int L, int b, int h, int vs, LAS unsigned char* lds) {
;     ...
;     auto stage_kt_v = [&](LAS float* gbn) {
;         if (isk) {
; #pragma unroll
;             for (int e = 0; e < 8; ++e) {
;                 v4u t;
;     ...
;                 if (e & 1) { t.x = (PKW(0) >> 16) | (PKW(1) & 0xffff0000u); t.y = (PKW(2) >> 16) | (PKW(3) & 0xffff0000u); t.z = (PKW(4) >> 16) | (PKW(5) & 0xffff0000u); t.w = (PKW(6) >> 16) | (PKW(7) & 0xffff0000u); }
;                 else { t.x = (PKW(0) & 0xffffu) | (PKW(1) << 16); t.y = (PKW(2) & 0xffffu) | (PKW(3) << 16); t.z = (PKW(4) & 0xffffu) | (PKW(5) << 16); t.w = (PKW(6) & 0xffffu) | (PKW(7) << 16); }
;     ...
;                 *(LAS v4u*)(lds + ML_KT + ((cgp & 31) * 8 + e) * 144 + ((w ^ (((cgp & 31) >> 1) & 7)) * 16)) = t; }
;         }
;         if (tid < 256) { const int s = tid >> 2, part = tid & 3; const float ws_ = gbn[FL_WST + s];
;             const unsigned xs[4] = {vraw.x, vraw.y, vraw.z, vraw.w};
; #pragma unroll
;             for (int e = 0; e < 8; ++e) { const unsigned wd = xs[e >> 1]; const float v = (e & 1) ? bfhi(wd) : bflo(wd);
;                 *(LAS bf16*)(lds + ML_VT + (part * 8 + e) * 144 + s * 2) = (bf16)((e & 1) ? (wd >> 16) : (wd & 0xffffu));
;                 *(LAS bf16*)(lds + ML_VWT + (part * 8 + e) * 144 + s * 2) = (bf16)(cvt_pk_bf16(v * ws_, 0.f) & 0xffffu); } }
;     ...
;         __syncthreads();
;         if (ch + 1 < 64) stage_kt_v(FL + ((ch + 1) & 1) * FL_GSZ);
.LBB0_552:
	s_and_b64 vcc, exec, s[34:35]
	s_waitcnt lgkmcnt(0)
	s_barrier
	s_cbranch_vccnz .LBB0_521
	s_waitcnt vmcnt(4)
	s_mov_b32 s4, 0xffff0000
	v_permlane32_swap_b32_e32 v6, v4
	v_permlane32_swap_b32_e32 v7, v5
	v_permlane32_swap_b32_e32 v10, v8
	v_permlane32_swap_b32_e32 v11, v9
	v_permlane32_swap_b32_e32 v14, v12
	v_permlane32_swap_b32_e32 v15, v13
	v_permlane32_swap_b32_e32 v18, v16
	v_permlane32_swap_b32_e32 v19, v17
	v_permlane32_swap_b32_e32 v22, v20
	v_permlane32_swap_b32_e32 v23, v21
	v_permlane32_swap_b32_e32 v26, v24
	v_permlane32_swap_b32_e32 v27, v25
	v_permlane32_swap_b32_e32 v30, v28
	v_permlane32_swap_b32_e32 v31, v29
	v_permlane32_swap_b32_e32 v34, v32
	v_permlane32_swap_b32_e32 v35, v33
	v_and_b32_e32 v64, 0xffff, v4
	v_and_b32_e32 v65, 0xffff, v12
	v_and_b32_e32 v66, 0xffff, v20
	v_and_b32_e32 v67, 0xffff, v28
	v_lshl_or_b32 v64, v8, 16, v64
	v_lshl_or_b32 v65, v16, 16, v65
	v_lshl_or_b32 v66, v24, 16, v66
	v_lshl_or_b32 v67, v32, 16, v67
	ds_write_b128 v249, v[64:67]
	v_lshrrev_b32_e32 v64, 16, v4
	v_lshrrev_b32_e32 v65, 16, v12
	v_lshrrev_b32_e32 v66, 16, v20
	v_lshrrev_b32_e32 v67, 16, v28
	v_and_or_b32 v64, v8, s4, v64
	v_and_or_b32 v65, v16, s4, v65
	v_and_or_b32 v66, v24, s4, v66
	v_and_or_b32 v67, v32, s4, v67
	ds_write_b128 v250, v[64:67]
	v_and_b32_e32 v64, 0xffff, v5
	v_and_b32_e32 v65, 0xffff, v13
	v_and_b32_e32 v66, 0xffff, v21
	v_and_b32_e32 v67, 0xffff, v29
	v_lshl_or_b32 v64, v9, 16, v64
	v_lshl_or_b32 v65, v17, 16, v65
	v_lshl_or_b32 v66, v25, 16, v66
	v_lshl_or_b32 v67, v33, 16, v67
	ds_write_b128 v251, v[64:67]
	v_lshrrev_b32_e32 v64, 16, v5
	v_lshrrev_b32_e32 v65, 16, v13
	v_lshrrev_b32_e32 v66, 16, v21
	v_lshrrev_b32_e32 v67, 16, v29
	v_and_or_b32 v64, v9, s4, v64
	v_and_or_b32 v65, v17, s4, v65
	v_and_or_b32 v66, v25, s4, v66
	v_and_or_b32 v67, v33, s4, v67
	ds_write_b128 v252, v[64:67]
.LBB0_555:
	s_and_saveexec_b64 s[34:35], s[6:7]
	s_cbranch_execz .LBB0_520
	s_bitcmp1_b32 s65, 0
	s_cselect_b32 s4, 0x5a0, 0
	v_add_u32_e32 v64, s4, v111
	ds_read_b32 v64, v64 offset:1024
	s_waitcnt vmcnt(4)
	v_lshlrev_b32_e32 v65, 16, v36
	v_add_u32_e32 v66, v112, v99
	ds_write_b16 v66, v36
	v_add_u32_e32 v66, v113, v99
	s_waitcnt lgkmcnt(1)
	v_mul_f32_e32 v65, v64, v65
	v_cvt_pk_bf16_f32 v65, v65, s0
	ds_write_b16 v66, v65
	v_and_b32_e32 v65, 0xffff0000, v36
	v_add_u32_e32 v66, v112, v100
	v_mul_f32_e32 v65, v64, v65
	ds_write_b16_d16_hi v66, v36
	v_cvt_pk_bf16_f32 v65, v65, s0
	v_add_u32_e32 v66, v113, v100
	ds_write_b16 v66, v65
	v_lshlrev_b32_e32 v65, 16, v37
	v_add_u32_e32 v66, v112, v101
	v_mul_f32_e32 v65, v64, v65
	ds_write_b16 v66, v37
	v_cvt_pk_bf16_f32 v65, v65, s0
	v_add_u32_e32 v66, v113, v101
	ds_write_b16 v66, v65
	v_and_b32_e32 v65, 0xffff0000, v37
	v_add_u32_e32 v66, v112, v102
	v_mul_f32_e32 v65, v64, v65
	ds_write_b16_d16_hi v66, v37
	v_cvt_pk_bf16_f32 v65, v65, s0
	v_add_u32_e32 v66, v113, v102
	ds_write_b16 v66, v65
	v_lshlrev_b32_e32 v65, 16, v38
	v_add_u32_e32 v66, v112, v103
	v_mul_f32_e32 v65, v64, v65
	ds_write_b16 v66, v38
	v_cvt_pk_bf16_f32 v65, v65, s0
	v_add_u32_e32 v66, v113, v103
	ds_write_b16 v66, v65
	v_and_b32_e32 v65, 0xffff0000, v38
	v_add_u32_e32 v66, v112, v104
	v_mul_f32_e32 v65, v64, v65
	ds_write_b16_d16_hi v66, v38
	v_cvt_pk_bf16_f32 v65, v65, s0
	v_add_u32_e32 v66, v113, v104
	ds_write_b16 v66, v65
	v_lshlrev_b32_e32 v65, 16, v39
	v_add_u32_e32 v66, v112, v105
	v_mul_f32_e32 v65, v64, v65
	ds_write_b16 v66, v39
	v_cvt_pk_bf16_f32 v65, v65, s0
	v_add_u32_e32 v66, v113, v105
	ds_write_b16 v66, v65
	v_and_b32_e32 v65, 0xffff0000, v39
	v_mul_f32_e32 v64, v64, v65
	v_add_u32_e32 v66, v112, v106
	v_cvt_pk_bf16_f32 v64, v64, s0
	v_add_u32_e32 v65, v113, v106
	ds_write_b16_d16_hi v66, v39
	ds_write_b16 v65, v64
	s_branch .LBB0_520

; #define LAS __attribute__((address_space(3)))
; template <class Epi, bool ALIGN_EPI>
; __device__ __forceinline__ void gemm_phase(LAS unsigned char* lds, const Gemm g, const StaticOrder& S, const Epi& E) {
;     ...
;             if (cur.pm != cpm) { cpm = cur.pm; const float* rp = E.rs_src();
; #pragma unroll
;                 for (int j = 0; j < 2; ++j) { const int q = lane + 64 * j; const int row = cur.pm * 256 + (q >> 6) * 128 + wr * 64 + (q & 63);
;                     const f32x4* p4 = (const f32x4*)(rp + (size_t)row * 16); const f32x4 t4 = (p4[0] + p4[1]) + (p4[2] + p4[3]);
;                     ((LAS float*)(lds + RSL_OFF))[wid * 128 + q] = rsqrtf(((t4[0] + t4[1]) + (t4[2] + t4[3])) * (1.0f / 1024.0f) + 1e-6f); } }
.LBB0_606:
	s_lshl_b32 s15, s39, 8
	s_cmp_eq_u32 s39, s23
	s_cbranch_scc1 .LBB0_608
	v_add_u32_e32 v156, s15, v159
	v_ashrrev_i32_e32 v157, 31, v156
	v_readlane_b32 s6, v254, 53
	v_lshlrev_b64 v[142:143], 6, v[156:157]
	v_readlane_b32 s7, v254, 54
	s_nop 1
	v_lshl_add_u64 v[162:163], s[6:7], 0, v[142:143]
	global_load_dwordx4 v[142:145], v[162:163], off offset:32
	global_load_dwordx4 v[146:149], v[162:163], off offset:48
	global_load_dwordx4 v[150:153], v[162:163], off
	global_load_dwordx4 v[180:183], v[162:163], off offset:16
	v_add_u32_e32 v200, 0x80, v156
	v_ashrrev_i32_e32 v201, 31, v200
	v_lshlrev_b64 v[200:201], 6, v[200:201]
	v_lshl_add_u64 v[202:203], s[6:7], 0, v[200:201]
	global_load_dwordx4 v[184:187], v[202:203], off offset:32
	global_load_dwordx4 v[188:191], v[202:203], off offset:48
	global_load_dwordx4 v[192:195], v[202:203], off
	global_load_dwordx4 v[196:199], v[202:203], off offset:16
	s_waitcnt vmcnt(4)
	v_pk_add_f32 v[144:145], v[144:145], v[148:149]
	v_pk_add_f32 v[142:143], v[142:143], v[146:147]
	v_pk_add_f32 v[152:153], v[152:153], v[182:183]
	v_pk_add_f32 v[150:151], v[150:151], v[180:181]
	v_pk_add_f32 v[144:145], v[152:153], v[144:145]
	v_pk_add_f32 v[142:143], v[150:151], v[142:143]
	s_nop 0
	v_pk_mov_b32 v[146:147], v[142:143], v[144:145] op_sel:[1,0]
	v_mov_b32_e32 v143, v145
	v_pk_add_f32 v[162:163], v[146:147], v[142:143]
	s_mov_b32 s6, 0x3a800000
	s_waitcnt vmcnt(2)
	v_pk_add_f32 v[144:145], v[186:187], v[190:191]
	v_pk_add_f32 v[142:143], v[184:185], v[188:189]
	s_waitcnt vmcnt(0)
	v_pk_add_f32 v[152:153], v[194:195], v[198:199]
	v_pk_add_f32 v[150:151], v[192:193], v[196:197]
	v_pk_add_f32 v[144:145], v[152:153], v[144:145]
	v_pk_add_f32 v[142:143], v[150:151], v[142:143]
	s_nop 0
	v_pk_mov_b32 v[146:147], v[142:143], v[144:145] op_sel:[1,0]
	v_mov_b32_e32 v143, v145
	v_pk_add_f32 v[142:143], v[146:147], v[142:143]
	v_mov_b32_e32 v145, v162
	v_mov_b32_e32 v144, v142
	v_mov_b32_e32 v162, v143
	v_pk_add_f32 v[142:143], v[144:145], v[162:163]
	s_nop 0
	v_pk_fma_f32 v[142:143], v[142:143], s[6:7], v[154:155] op_sel_hi:[1,0,0]
	s_mov_b32 s6, 0x800000
	v_mul_f32_e32 v0, 0x4b800000, v143
	v_cmp_gt_f32_e32 vcc, s6, v142
	v_cmp_gt_f32_e64 s[6:7], s6, v143
	s_nop 1
	v_cndmask_b32_e64 v0, v143, v0, s[6:7]
	v_rsq_f32_e32 v0, v0
	s_nop 0
	v_mul_f32_e32 v143, 0x45800000, v0
	v_cndmask_b32_e64 v0, v0, v143, s[6:7]
	v_mul_f32_e32 v143, 0x4b800000, v142
	v_cndmask_b32_e32 v142, v142, v143, vcc
	v_rsq_f32_e32 v142, v142
	s_nop 0
	v_mul_f32_e32 v143, 0x45800000, v142
	v_cndmask_b32_e32 v142, v142, v143, vcc
	ds_write2st64_b32 v161, v0, v142 offset1:1

; #define LAS __attribute__((address_space(3)))
; template <class Epi, bool ALIGN_EPI>
; __device__ __forceinline__ void gemm_phase(LAS unsigned char* lds, const Gemm g, const StaticOrder& S, const Epi& E) {
;     ...
;             if (cur.pm != cpm) { cpm = cur.pm; const float* rp = E.rs_src();
; #pragma unroll
;                 for (int j = 0; j < 2; ++j) { const int q = lane + 64 * j; const int row = cur.pm * 256 + (q >> 6) * 128 + wr * 64 + (q & 63);
;                     const f32x4* p4 = (const f32x4*)(rp + (size_t)row * 16); const f32x4 t4 = (p4[0] + p4[1]) + (p4[2] + p4[3]);
;                     ((LAS float*)(lds + RSL_OFF))[wid * 128 + q] = rsqrtf(((t4[0] + t4[1]) + (t4[2] + t4[3])) * (1.0f / 1024.0f) + 1e-6f); } }
.LBB0_852:
	s_lshl_b32 s1, s29, 8
	s_cmp_eq_u32 s29, s31
	s_cbranch_scc1 .LBB0_854
	v_add_u32_e32 v152, s1, v145
	v_ashrrev_i32_e32 v153, 31, v152
	v_readlane_b32 s6, v254, 51
	v_lshlrev_b64 v[140:141], 6, v[152:153]
	v_readlane_b32 s7, v254, 52
	s_nop 1
	v_lshl_add_u64 v[160:161], s[6:7], 0, v[140:141]
	global_load_dwordx4 v[140:143], v[160:161], off offset:32
	global_load_dwordx4 v[148:151], v[160:161], off offset:48
	global_load_dwordx4 v[156:159], v[160:161], off
	global_load_dwordx4 v[180:183], v[160:161], off offset:16
	v_add_u32_e32 v200, 0x80, v152
	v_ashrrev_i32_e32 v201, 31, v200
	v_lshlrev_b64 v[200:201], 6, v[200:201]
	v_lshl_add_u64 v[202:203], s[6:7], 0, v[200:201]
	global_load_dwordx4 v[184:187], v[202:203], off offset:32
	global_load_dwordx4 v[188:191], v[202:203], off offset:48
	global_load_dwordx4 v[192:195], v[202:203], off
	global_load_dwordx4 v[196:199], v[202:203], off offset:16
	s_waitcnt vmcnt(4)
	v_pk_add_f32 v[142:143], v[142:143], v[150:151]
	v_pk_add_f32 v[140:141], v[140:141], v[148:149]
	v_pk_add_f32 v[158:159], v[158:159], v[182:183]
	v_pk_add_f32 v[156:157], v[156:157], v[180:181]
	v_pk_add_f32 v[142:143], v[158:159], v[142:143]
	v_pk_add_f32 v[140:141], v[156:157], v[140:141]
	s_nop 0
	v_pk_mov_b32 v[148:149], v[140:141], v[142:143] op_sel:[1,0]
	v_mov_b32_e32 v141, v143
	v_pk_add_f32 v[160:161], v[148:149], v[140:141]
	s_mov_b32 s6, 0x3a800000
	s_waitcnt vmcnt(2)
	v_pk_add_f32 v[142:143], v[186:187], v[190:191]
	v_pk_add_f32 v[140:141], v[184:185], v[188:189]
	s_waitcnt vmcnt(0)
	v_pk_add_f32 v[152:153], v[194:195], v[198:199]
	v_pk_add_f32 v[156:157], v[192:193], v[196:197]
	v_pk_add_f32 v[142:143], v[152:153], v[142:143]
	v_pk_add_f32 v[140:141], v[156:157], v[140:141]
	s_nop 0
	v_pk_mov_b32 v[148:149], v[140:141], v[142:143] op_sel:[1,0]
	v_mov_b32_e32 v141, v143
	v_pk_add_f32 v[140:141], v[148:149], v[140:141]
	v_mov_b32_e32 v143, v160
	v_mov_b32_e32 v142, v140
	v_mov_b32_e32 v160, v141
	v_pk_add_f32 v[140:141], v[142:143], v[160:161]
	s_nop 0
	v_pk_fma_f32 v[140:141], v[140:141], s[6:7], v[154:155] op_sel_hi:[1,0,0]
	s_mov_b32 s6, 0x800000
	v_mul_f32_e32 v142, 0x4b800000, v141
	v_cmp_gt_f32_e32 vcc, s6, v140
	v_cmp_gt_f32_e64 s[6:7], s6, v141
	s_nop 1
	v_cndmask_b32_e64 v141, v141, v142, s[6:7]
	v_rsq_f32_e32 v141, v141
	s_nop 0
	v_mul_f32_e32 v142, 0x45800000, v141
	v_cndmask_b32_e64 v141, v141, v142, s[6:7]
	v_mul_f32_e32 v142, 0x4b800000, v140
	v_cndmask_b32_e32 v140, v140, v142, vcc
	v_rsq_f32_e32 v140, v140
	s_nop 0
	v_mul_f32_e32 v142, 0x45800000, v140
	v_cndmask_b32_e32 v140, v140, v142, vcc
	ds_write2st64_b32 v147, v141, v140 offset1:1
